# v49: v48 + phase_fix distributed by XCD ownership (grid 256) so the fix->down boundary is an XCD-local barrier as well
# speedup vs baseline: 1.0130x; 1.0053x over previous
.LBB0_851:
	s_or_b64 exec, exec, s[2:3]
	s_waitcnt lgkmcnt(0)
	v_mov_b32_e32 v0, v234
	v_readlane_b32 s2, v253, 8
	s_mov_b32 s97, 0x15ffff
	v_readlane_b32 s96, v254, 46
	s_cmp_lg_u32 s46, 0x100
	s_cbranch_scc1 .Lfx_gen
	v_readlane_b32 s98, v254, 59
	s_and_b32 s99, s98, 7
	s_mul_i32 s99, s99, 0x2c000
	s_lshr_b32 s98, s98, 3
	s_lshl_b32 s98, s98, 9
	s_add_i32 s2, s99, s98
	s_add_i32 s97, s99, 0x2bfff
	s_lshr_b32 s96, s96, 3
.Lfx_gen:
	s_barrier
	s_mov_b32 s0, 0x160000
	v_add_u32_e32 v6, s2, v0
	v_cmp_gt_i32_e32 vcc, s0, v6
	s_and_saveexec_b64 s[34:35], vcc
	s_cbranch_execz .LBB0_870
	s_mov_b64 s[42:43], 0
	s_branch .LBB0_855

.LBB0_854:
	s_or_b64 exec, exec, s[4:5]
	s_waitcnt vmcnt(2)
	v_mul_f32_e32 v4, v9, v14
	v_fmac_f32_e32 v4, v11, v13
	s_waitcnt vmcnt(1)
	v_fmac_f32_e32 v4, v10, v15
	s_waitcnt vmcnt(0)
	v_add_f32_e32 v13, v16, v4
	v_lshlrev_b64 v[4:5], 2, v[200:201]
	v_or_b32_e32 v7, v8, v7
	v_lshl_add_u64 v[8:9], s[38:39], 0, v[4:5]
	v_add_co_u32_e32 v14, vcc, 0x5000, v8
	s_mov_b32 s2, 0xb000
	s_nop 0
	v_addc_co_u32_e32 v15, vcc, 0, v9, vcc
	global_load_dword v10, v[8:9], off
	s_nop 0
	global_load_dword v14, v[14:15], off offset:2048
	v_add_co_u32_e32 v8, vcc, s2, v8
	s_nop 1
	v_addc_co_u32_e32 v9, vcc, 0, v9, vcc
	global_load_dword v11, v[8:9], off
	s_waitcnt vmcnt(0)
	v_pk_mul_f32 v[2:3], v[2:3], v[10:11]
	s_nop 0
	v_fma_f32 v2, v12, v14, v2
	v_add_f32_e32 v8, v2, v3
	v_lshl_add_u64 v[2:3], s[40:41], 0, v[4:5]
	global_load_dword v2, v[2:3], off
	v_mul_f32_e32 v3, 0xbfb8aa3b, v13
	v_exp_f32_e32 v3, v3
	s_waitcnt vmcnt(0)
	v_add_f32_e32 v2, v2, v8
	v_add_f32_e32 v3, 1.0, v3
	v_rcp_f32_e32 v3, v3
	s_nop 0
	v_mul_f32_e32 v3, v13, v3
	v_mul_f32_e32 v2, v3, v2
	v_cvt_pk_bf16_f32 v4, v2, s0
	v_mov_b64_e32 v[2:3], s[18:19]
	s_movk_i32 s0, 0x1600
	v_mad_i64_i32 v[2:3], s[2:3], v7, s0, v[2:3]
	s_mov_b32 s0, s96
	s_mov_b32 s2, s97
	v_lshl_add_u64 v[0:1], v[0:1], 1, v[2:3]
	v_add_u32_e32 v6, s0, v6
	v_cmp_lt_i32_e32 vcc, s2, v6
	s_or_b64 s[42:43], vcc, s[42:43]
	global_store_short v[0:1], v4, off
	s_andn2_b64 exec, exec, s[42:43]
	s_cbranch_execz .LBB0_870

.LBB0_907:
	s_andn2_saveexec_b64 s[4:5], s[4:5]
	s_cbranch_execz .LBB0_927
	s_mov_b64 s[4:5], exec
	v_readlane_b32 s99, v255, 40
	s_bitcmp1_b32 s99, 0
	s_cbranch_scc0 .Lxl_7_full
	s_cmp_eq_u32 s46, 0x100
	s_cbranch_scc1 .Lxl_7
